# phase 3: scan blocks take the 12th-round in-proj tiles after their scan (11 rounds for the other 448 blocks); B1 norm loop batched LDS reads
# baseline (speedup 1.0000x reference)
; DI void phase_inproj(const Params& p, int l, bool partB, int skipb, char* smem) {
;   const int ntn = partB ? 13 : 20;
;   const int ntiles = 256 * ntn;
;   const int per = ntiles >> 3;
;   const int vblk = blockIdx.x - skipb, nvb = gridDim.x - skipb;
;   for (int idx = vblk >> 3; idx < per; idx += nvb >> 3) {
;     const int t = (vblk & 7) * per + idx;
;     const int mt = t / ntn; int tn = t % ntn;
;     if (partB) tn += 12; else if (tn >= 12) tn += 13;
;     inproj_tile(p, l, mt, tn, smem);
;   }
; }
; __global__ void __launch_bounds__(256, 2) mega(Params p, int ph_lo, int ph_hi) {
;     ...
;       case 3: if (PHASE_ONLY >= 0 && PHASE_ONLY != 3) break; {
;         const int nb2 = gridDim.x >= 128 ? 64 : 0;
;         if ((int)blockIdx.x < nb2) phaseB2(p, blockIdx.x, smem, 0, B2_S1);
;         else phase_inproj(p, l, false, nb2, smem);
;         if (nb2 == 0) for (int u = blockIdx.x; u < 64; u += gridDim.x) phaseB2(p, u, smem, 0, B2_S1);
;       } break;
.LBB0_1:
	s_load_dwordx16 s[4:19], s[0:1], 0x0
	s_load_dwordx8 s[20:27], s[0:1], 0x180
	v_and_b32_e32 v230, 0x3ff, v0
	v_and_b32_e32 v0, 0x3fffffff, v0
	s_movk_i32 s97, 0x1000
	s_waitcnt lgkmcnt(0)
	v_writelane_b32 v250, s4, 2
	s_movk_i32 s33, 0x7f
	s_mov_b32 s96, 0x3e38aa3b
	v_writelane_b32 v250, s5, 3
	v_writelane_b32 v250, s6, 4
	v_writelane_b32 v250, s7, 5
	v_writelane_b32 v250, s8, 6
	v_writelane_b32 v250, s9, 7
	v_writelane_b32 v250, s10, 8
	v_writelane_b32 v250, s11, 9
	v_writelane_b32 v250, s12, 10
	v_writelane_b32 v250, s13, 11
	v_writelane_b32 v250, s14, 12
	v_writelane_b32 v250, s15, 13
	v_writelane_b32 v250, s16, 14
	v_writelane_b32 v250, s17, 15
	v_writelane_b32 v250, s18, 16
	v_writelane_b32 v250, s19, 17
	s_load_dwordx16 s[4:19], s[0:1], 0x40
	v_mov_b32_e32 v227, 0x358637bd
	v_mov_b32_e32 v232, 0x10900
	v_mov_b32_e32 v233, 0x10a00
	v_mov_b32_e32 v247, 0x10910
	s_waitcnt lgkmcnt(0)
	v_writelane_b32 v250, s4, 18
	v_mov_b32_e32 v245, 0x10920
	v_mov_b32_e32 v246, 0x10930
	v_writelane_b32 v250, s5, 19
	v_writelane_b32 v250, s6, 20
	v_writelane_b32 v250, s7, 21
	v_writelane_b32 v250, s8, 22
	v_writelane_b32 v250, s9, 23
	v_writelane_b32 v250, s10, 24
	v_writelane_b32 v250, s11, 25
	v_writelane_b32 v250, s12, 26
	v_writelane_b32 v250, s13, 27
	v_writelane_b32 v250, s14, 28
	v_writelane_b32 v250, s15, 29
	v_writelane_b32 v250, s16, 30
	v_writelane_b32 v250, s17, 31
	v_writelane_b32 v250, s18, 32
	v_writelane_b32 v250, s19, 33
	s_load_dwordx16 s[68:83], s[0:1], 0x80
	s_load_dwordx16 s[36:51], s[0:1], 0xc0
	s_load_dwordx16 s[4:19], s[0:1], 0x100
	v_mov_b32_e32 v224, 0x10940
	v_mov_b32_e32 v225, 0x10950
	v_mov_b32_e32 v248, 0x10960
	v_mov_b32_e32 v226, 0x10970
	s_waitcnt lgkmcnt(0)
	v_writelane_b32 v250, s4, 34
	v_mov_b32_e32 v228, 0x10980
	v_mov_b32_e32 v229, 0x10990
	v_writelane_b32 v250, s5, 35
	v_writelane_b32 v250, s6, 36
	v_writelane_b32 v250, s7, 37
	v_writelane_b32 v250, s8, 38
	v_writelane_b32 v250, s9, 39
	v_writelane_b32 v250, s10, 40
	v_writelane_b32 v250, s11, 41
	v_writelane_b32 v250, s12, 42
	v_writelane_b32 v250, s13, 43
	v_writelane_b32 v250, s14, 44
	v_writelane_b32 v250, s15, 45
	v_writelane_b32 v250, s16, 46
	v_writelane_b32 v250, s17, 47
	v_writelane_b32 v250, s18, 48
	v_writelane_b32 v250, s19, 49
	s_load_dwordx16 s[52:67], s[0:1], 0x140
	s_load_dwordx4 s[4:7], s[0:1], 0x1a0
	s_load_dword s18, s[0:1], 0x1b8
	s_mov_b32 s16, s2
	s_mov_b32 s15, 0
	v_mov_b32_e32 v231, 0x109a0
	s_waitcnt lgkmcnt(0)
	s_cmpk_eq_u32 s18, 0x200
	s_cbranch_scc1 .Lrb_on
	s_cmpk_gt_u32 s18, 0x7f
	s_cselect_b32 s98, 64, 0
	s_sub_i32 s98, s18, s98
	s_lshr_b32 s98, s98, 3
	s_movk_i32 s99, 0x280
	s_nop 0
	v_writelane_b32 v255, s98, 20
	v_writelane_b32 v255, s99, 21
	s_mov_b32 s99, 0x7fffffff
	s_nop 0
	v_writelane_b32 v255, s99, 22
	s_branch .Lrb_done
.Lrb_on:
	s_cmpk_lt_u32 s101, 0x40
	s_cbranch_scc1 .Lrb_b2
	s_movk_i32 s98, 56
	s_movk_i32 s99, 0x268
	s_nop 0
	v_writelane_b32 v255, s98, 20
	v_writelane_b32 v255, s99, 21
	s_mov_b32 s99, 0x7fffffff
	s_nop 0
	v_writelane_b32 v255, s99, 22
	s_branch .Lrb_done
.Lrb_b2:
	s_lshr_b32 s98, s101, 3
	s_mul_i32 s98, s98, 3
	s_addk_i32 s98, 0x268
	s_add_i32 s99, s98, 3
	s_nop 0
	v_writelane_b32 v255, s98, 22
	v_writelane_b32 v255, s99, 21
	s_mov_b32 s98, 1
	s_nop 0
	v_writelane_b32 v255, s98, 20
.Lrb_done:
	v_writelane_b32 v250, s4, 50
	v_mov_b32_e32 v239, 0x109b0
	v_mov_b32_e32 v240, 0x109c0
	v_writelane_b32 v250, s5, 51
	v_writelane_b32 v250, s6, 52
	v_writelane_b32 v250, s7, 53
	s_add_u32 s4, s0, 0x1b8
	s_addc_u32 s5, s1, 0
	v_writelane_b32 v250, s4, 54
	s_lshr_b32 s0, s2, 3
	s_cmpk_lt_u32 s2, 0x1000
	v_writelane_b32 v250, s5, 55
	v_writelane_b32 v250, s0, 56
	s_cselect_b64 s[0:1], -1, 0
	v_writelane_b32 v250, s0, 57
	s_lshl_b32 s94, s18, 2
	v_mov_b32_e32 v241, 0x109d0
	v_writelane_b32 v250, s1, 58
	s_lshl_b32 s0, s2, 9
	s_and_b32 s0, s0, 0xe00
	v_writelane_b32 v250, s0, 59
	s_lshr_b32 s0, s18, 3
	v_writelane_b32 v250, s0, 60
	s_lshl_b32 s0, s2, 2
	v_writelane_b32 v250, s0, 61
	s_lshr_b32 s0, s18, 1
	s_sub_i32 s0, s2, s0
	s_lshl_b32 s1, s0, 2
	s_cmp_gt_i32 s0, -1
	v_writelane_b32 v250, s1, 62
	s_cselect_b64 s[0:1], -1, 0
	v_writelane_b32 v250, s0, 63
	v_mov_b32_e32 v242, 0x109e0
	v_mov_b32_e32 v243, 0x109f0
	v_writelane_b32 v251, s1, 0
	s_lshl_b32 s0, s18, 1
	s_and_b32 s0, s0, -4
	s_cmpk_lt_u32 s2, 0x800
	v_writelane_b32 v251, s0, 1
	s_cselect_b64 s[0:1], -1, 0
	v_writelane_b32 v251, s0, 2
	v_mov_b32_e32 v234, 0x7f
	v_mov_b32_e32 v235, 0xf149f2ca
	v_writelane_b32 v251, s1, 3
	s_lshl_b32 s0, s2, 8
	s_and_b32 s0, s0, 0x700
	s_cmpk_lt_u32 s18, 0x80
	s_cselect_b64 s[4:5], -1, 0
	s_cmpk_gt_u32 s18, 0x7f
	s_cselect_b64 s[2:3], -1, 0
	v_writelane_b32 v251, s0, 4
	s_and_b64 s[0:1], s[2:3], exec
	s_cselect_b32 s19, 64, 0
	s_cselect_b32 s11, 0xffffffc0, 0
	s_sub_i32 s14, s18, s19
	s_cmp_gt_i32 s14, 64
	s_cselect_b64 s[0:1], -1, 0
	v_writelane_b32 v251, s2, 5
	s_and_b64 s[8:9], s[2:3], s[0:1]
	s_and_b64 s[0:1], s[8:9], exec
	v_writelane_b32 v251, s3, 6
	s_cselect_b32 s3, 0x300, 0
	s_abs_i32 s2, s14
	v_cvt_f32_u32_e32 v1, s2
	s_mul_i32 s10, s19, -3
	s_sub_i32 s6, 0, s2
	s_sub_i32 s0, s10, s3
	v_rcp_iflag_f32_e32 v1, v1
	s_addk_i32 s0, 0x1000
	s_ashr_i32 s1, s0, 31
	s_abs_i32 s0, s0
	v_mul_f32_e32 v1, 0x4f7ffffe, v1
	v_cvt_u32_f32_e32 v1, v1
	v_mov_b32_e32 v236, 0x4e6e6b28
	v_mov_b32_e32 v237, 0x10800
	v_mov_b32_e32 v238, 0xd00
	v_readfirstlane_b32 s7, v1
	s_mul_i32 s6, s6, s7
	s_mul_hi_u32 s6, s7, s6
	s_add_i32 s7, s7, s6
	s_mul_hi_u32 s6, s0, s7
	s_mul_i32 s6, s6, s2
	s_sub_i32 s0, s0, s6
	s_sub_i32 s6, s0, s2
	s_cmp_ge_u32 s0, s2
	s_cselect_b32 s0, s6, s0
	s_sub_i32 s6, s0, s2
	s_cmp_ge_u32 s0, s2
; __global__ void __launch_bounds__(256, 2) mega(Params p, int ph_lo, int ph_hi) {
;     ...
;         const int nb2 = gridDim.x >= 128 ? 64 : 0;
;         const int nvb = gridDim.x - nb2;
;         const int ubeg = (nb2 && (int)gridDim.x - nb2 - 64 > 0) ? A1_EARLY : 0;
;         const int usplit = nb2 ? ubeg + (4096 - ubeg - 3 * nb2) / nvb * nvb : 4096;
	s_cselect_b32 s0, s6, s0
	s_xor_b32 s0, s0, s1
	s_sub_i32 s0, s1, s0
	s_add_i32 s10, s10, s0
	s_cmp_ge_i32 s16, s19
	s_cselect_b64 s[0:1], -1, 0
	s_sub_i32 s28, s16, s19
	v_writelane_b32 v251, s0, 7
	s_cmp_lt_i32 s28, 32
	v_mov_b32_e32 v1, 0
	v_writelane_b32 v251, s1, 8
	s_cselect_b64 s[0:1], -1, 0
	v_writelane_b32 v251, s0, 9
	s_ashr_i32 s17, s16, 31
	s_ashr_i32 s2, s16, 2
	v_writelane_b32 v251, s1, 10
	s_add_i32 s0, s3, s28
	v_writelane_b32 v251, s0, 11
	s_and_b32 s29, s16, 3
	s_lshl_b64 s[0:1], s[16:17], 16
	s_add_u32 s0, s60, s0
	s_addc_u32 s1, s61, s1
	v_writelane_b32 v251, s0, 12
	v_mov_b32_e32 v244, 0x10804
	s_nop 0
	v_writelane_b32 v251, s1, 13
	s_lshl_b32 s0, s2, 5
	v_writelane_b32 v251, s0, 14
	s_lshl_b32 s0, s2, 7
	s_or_b32 s0, s0, s29
	s_or_b32 s6, s0, 0x60
	s_ashr_i32 s7, s6, 31
	s_lshl_b64 s[12:13], s[6:7], 13
	s_lshl_b64 s[6:7], s[6:7], 14
	s_add_u32 s30, s62, s6
	s_addc_u32 s31, s63, s7
	v_writelane_b32 v251, s30, 15
	s_nop 1
	v_writelane_b32 v251, s31, 16
	s_add_u32 s30, s64, s6
	s_addc_u32 s31, s65, s7
	v_writelane_b32 v251, s30, 17
	s_nop 1
	v_writelane_b32 v251, s31, 18
	s_add_u32 s30, s66, s6
	s_addc_u32 s31, s67, s7
	v_writelane_b32 v251, s30, 19
	s_add_u32 s12, s20, s12
	s_addc_u32 s13, s21, s13
	v_writelane_b32 v251, s31, 20
	v_writelane_b32 v251, s12, 21
	s_add_u32 s6, s22, s6
	s_addc_u32 s7, s23, s7
	v_writelane_b32 v251, s13, 22
	s_lshl_b32 s2, s2, 11
	v_writelane_b32 v251, s6, 23
	s_cmp_lt_i32 s16, 64
	s_nop 0
	v_writelane_b32 v251, s7, 24
	s_cselect_b64 s[6:7], -1, 0
	s_cmpk_lt_i32 s28, 0x440
	s_cselect_b64 s[12:13], -1, 0
	v_writelane_b32 v251, s12, 25
	s_cmp_lg_u64 s[40:41], 0
	s_nop 0
	v_writelane_b32 v251, s13, 26
	s_cselect_b64 s[12:13], -1, 0
	s_add_i32 s1, s11, s18
	v_writelane_b32 v251, s12, 27
	s_cmp_gt_i32 s28, 63
	s_nop 0
	v_writelane_b32 v251, s13, 28
	s_cselect_b64 s[12:13], -1, 0
	v_writelane_b32 v251, s1, 29
	s_and_b64 s[8:9], s[8:9], s[12:13]
	v_writelane_b32 v251, s8, 30
	s_sub_i32 s1, s14, 64
	s_nop 0
	v_writelane_b32 v251, s9, 31
	v_writelane_b32 v251, s1, 32
	s_sub_i32 s1, s28, 64
	s_cmpk_lt_u32 s1, 0x300
	v_writelane_b32 v251, s1, 33
	s_cselect_b64 s[8:9], -1, 0
	v_writelane_b32 v251, s8, 34
	s_nop 1
	v_writelane_b32 v251, s9, 35
	s_or_b32 s8, s0, 0x4c
	s_ashr_i32 s9, s8, 31
	s_lshl_b64 s[12:13], s[8:9], 13
	s_lshl_b64 s[8:9], s[8:9], 14
	s_add_u32 s30, s62, s8
	s_addc_u32 s31, s63, s9
	v_writelane_b32 v251, s30, 36
	s_nop 1
	v_writelane_b32 v251, s31, 37
	s_add_u32 s30, s64, s8
	s_addc_u32 s31, s65, s9
	v_writelane_b32 v251, s30, 38
	s_nop 1
	v_writelane_b32 v251, s31, 39
	s_add_u32 s30, s66, s8
	s_addc_u32 s31, s67, s9
	v_writelane_b32 v251, s30, 40
	s_add_u32 s12, s20, s12
	s_addc_u32 s13, s21, s13
	v_writelane_b32 v251, s31, 41
	v_writelane_b32 v251, s12, 42
	s_add_u32 s8, s22, s8
	s_addc_u32 s9, s23, s9
	v_writelane_b32 v251, s13, 43
	v_writelane_b32 v251, s8, 44
	s_cmpk_lt_u32 s28, 0x1400
	s_nop 0
	v_writelane_b32 v251, s9, 45
	s_cselect_b64 s[8:9], -1, 0
	v_writelane_b32 v251, s8, 46
	s_lshr_b32 s1, s28, 3
	s_and_b32 s11, s16, 7
	v_writelane_b32 v251, s9, 47
	v_writelane_b32 v251, s28, 48
	v_writelane_b32 v251, s1, 49
	s_mul_i32 s1, s11, 0x280
	v_writelane_b32 v251, s1, 50
	v_writelane_b32 v251, s14, 51
	s_ashr_i32 s1, s14, 3
	v_writelane_b32 v251, s1, 52
	s_ashr_i32 s1, s0, 31
	s_lshl_b64 s[8:9], s[0:1], 13
	s_lshl_b64 s[12:13], s[0:1], 14
	s_add_u32 s30, s62, s12
	s_addc_u32 s31, s63, s13
	v_writelane_b32 v251, s30, 53
	s_nop 1
	v_writelane_b32 v251, s31, 54
	s_add_u32 s30, s64, s12
	s_addc_u32 s31, s65, s13
	v_writelane_b32 v251, s30, 55
	s_nop 1
	v_writelane_b32 v251, s31, 56
	s_add_u32 s30, s66, s12
	s_addc_u32 s31, s67, s13
	v_writelane_b32 v251, s30, 57
	s_add_u32 s8, s20, s8
	s_addc_u32 s9, s21, s9
	v_writelane_b32 v251, s31, 58
	v_writelane_b32 v251, s8, 59
	s_nop 1
	v_writelane_b32 v251, s9, 60
	s_add_u32 s8, s22, s12
	s_addc_u32 s9, s23, s13
	v_writelane_b32 v251, s8, 61
	s_cmpk_lt_i32 s16, 0x800
	s_nop 0
	v_writelane_b32 v251, s9, 62
	s_cselect_b64 s[8:9], -1, 0
	s_ashr_i32 s1, s16, 3
	v_writelane_b32 v251, s8, 63
	s_cmpk_lt_i32 s1, 0x1a0
	s_nop 0
	v_writelane_b32 v252, s9, 0
	v_writelane_b32 v252, s1, 1
	s_cselect_b64 s[8:9], -1, 0
	v_writelane_b32 v252, s8, 2
	s_mul_i32 s1, s11, 0x1a0
	s_add_i32 s11, s16, 0xe0
	v_writelane_b32 v252, s9, 3
	v_writelane_b32 v252, s1, 4
	s_ashr_i32 s1, s18, 3
	v_writelane_b32 v252, s1, 5
	s_add_i32 s1, s18, -1
	v_writelane_b32 v252, s1, 6
	s_add_i32 s1, s16, 64
	s_add_i32 s8, s16, 0x60
	s_add_i32 s9, s16, 0x50
	s_add_u32 s12, s80, 0x100000
	s_addc_u32 s13, s81, 0
	v_writelane_b32 v252, s12, 7
	s_nop 1
	v_writelane_b32 v252, s13, 8
	s_add_i32 s12, s16, 0x58
	s_add_u32 s30, s82, 0x10000
	v_writelane_b32 v252, s68, 9
	s_addc_u32 s31, s83, 0
	s_and_b64 s[4:5], s[4:5], s[6:7]
	v_writelane_b32 v252, s69, 10
	v_writelane_b32 v252, s70, 11
	v_writelane_b32 v252, s71, 12
	v_writelane_b32 v252, s72, 13
	v_writelane_b32 v252, s73, 14
	v_writelane_b32 v252, s74, 15
	v_writelane_b32 v252, s75, 16
	v_writelane_b32 v252, s76, 17
	v_writelane_b32 v252, s77, 18
	v_writelane_b32 v252, s78, 19
	v_writelane_b32 v252, s79, 20
	v_writelane_b32 v252, s80, 21
	v_writelane_b32 v252, s81, 22
	v_writelane_b32 v252, s82, 23
	v_writelane_b32 v252, s83, 24
	v_writelane_b32 v252, s30, 25
	s_add_i32 s13, s16, 0x160
	s_add_i32 s14, s16, 0xc8
	v_writelane_b32 v252, s31, 26
	v_cmp_eq_u32_e64 s[30:31], 0, v0
	v_cvt_f32_u32_e32 v0, s18
	s_movk_i32 s76, 0x90
	v_writelane_b32 v252, s30, 27
	s_movk_i32 s77, 0x200
	v_rcp_iflag_f32_e32 v0, v0
	v_writelane_b32 v252, s31, 28
	v_writelane_b32 v252, s4, 29
	s_movk_i32 s79, 0x210
	v_mul_f32_e32 v0, 0x4f7ffffe, v0
	v_cvt_u32_f32_e32 v0, v0
; #define TIDX (tid_launder())
; DI void tr_job(const float* __restrict__ src, int ld, int K, int Nsrc, bool map, bf16_t* __restrict__ dst, int Nrows,
;                float* lds, int rot) {
;   const int ntk = K / 64, ntiles = (Nrows / 64) * ntk;
;   const int vb = (blockIdx.x + rot) % gridDim.x;
;   const int tx = TIDX & 63, ty = TIDX >> 6;
;   for (int t = vb; t < ntiles; t += gridDim.x) {
; DI void phase0(const Params& p, int l, char* smem) {
;   float* lds = (float*)smem;
;   if (l == 0 && blockIdx.x == gridDim.x - 1) build_lut(p, p.lutg);
;   tr_job(p.w_in + (size_t)l * 1024 * 7260, 7260, 1024, 7260, true, p.wt_in, 7296, lds, 0);
;   tr_job(p.a_w_ukv + (size_t)l * 128 * 512, 512, 128, 512, false, p.wt_ukv, 512, lds, 64);
;   for (int kv = 0; kv < 2; ++kv) {
;     tr_job(p.c_phi_w1 + ((size_t)l * 2 + kv) * 2048 * 256, 256, 2048, 256, false, p.wt_phi1 + (size_t)kv * 256 * 2048, 256, lds, 96 + kv * 128);
;     tr_job(p.c_phi_w2 + ((size_t)l * 2 + kv) * 256 * 64, 64, 256, 64, false, p.wt_phi2 + (size_t)kv * 128 * 256, 128, lds, 80 + kv * 8);
;   }
;   tr_job(p.w_branch + (size_t)l * 1024 * 1024, 1024, 1024, 1024, false, p.wt_br, 1024, lds, 352);
;   tr_job(p.w_out + (size_t)l * 1024 * 1024, 1024, 1024, 1024, false, p.wt_out, 1024, lds, 96);
;   {
;     const int vb = (blockIdx.x + 200) % gridDim.x;
;     for (int j = vb; j < 16; j += gridDim.x) {
	v_writelane_b32 v252, s5, 30
	s_add_i32 s4, s10, 0x1000
	v_writelane_b32 v252, s4, 31
	s_sub_i32 s4, 0, s18
	v_readfirstlane_b32 s5, v0
	s_mul_i32 s4, s4, s5
	s_mul_hi_u32 s4, s5, s4
	s_add_i32 s5, s5, s4
	s_mul_hi_u32 s4, s16, s5
	s_mul_i32 s4, s4, s18
	s_sub_i32 s4, s16, s4
	s_sub_i32 s6, s4, s18
	s_cmp_ge_u32 s4, s18
	s_cselect_b32 s4, s6, s4
	s_sub_i32 s6, s4, s18
	s_cmp_ge_u32 s4, s18
	s_cselect_b32 s4, s6, s4
	v_writelane_b32 v252, s4, 32
	s_cmpk_lt_i32 s4, 0x720
	s_mul_hi_u32 s4, s1, s5
	s_mul_i32 s4, s4, s18
	s_cselect_b64 s[6:7], -1, 0
	s_sub_i32 s1, s1, s4
	s_sub_i32 s4, s1, s18
	s_cmp_ge_u32 s1, s18
	s_cselect_b32 s1, s4, s1
	s_sub_i32 s4, s1, s18
	v_writelane_b32 v252, s6, 33
	s_cmp_ge_u32 s1, s18
	s_cselect_b32 s1, s4, s1
	v_writelane_b32 v252, s7, 34
	v_writelane_b32 v252, s1, 35
	s_cmp_lt_i32 s1, 16
	s_mul_hi_u32 s1, s8, s5
	s_mul_i32 s1, s1, s18
	s_cselect_b64 s[6:7], -1, 0
	s_sub_i32 s1, s8, s1
	s_sub_i32 s4, s1, s18
	s_cmp_ge_u32 s1, s18
	s_cselect_b32 s1, s4, s1
	s_sub_i32 s4, s1, s18
	v_writelane_b32 v252, s6, 36
	s_cmp_ge_u32 s1, s18
	v_mbcnt_lo_u32_b32 v0, -1, 0
	v_writelane_b32 v252, s7, 37
	s_cselect_b32 s6, s4, s1
	s_mul_hi_u32 s1, s9, s5
	s_cmpk_lt_i32 s6, 0x80
	s_mul_i32 s1, s1, s18
	s_cselect_b64 s[30:31], -1, 0
	s_sub_i32 s1, s9, s1
	s_sub_i32 s4, s1, s18
	s_cmp_ge_u32 s1, s18
	s_cselect_b32 s1, s4, s1
	s_sub_i32 s4, s1, s18
	v_writelane_b32 v252, s30, 38
	s_cmp_ge_u32 s1, s18
	s_cselect_b32 s1, s4, s1
	v_writelane_b32 v252, s31, 39
	v_writelane_b32 v252, s1, 40
	s_cmp_lt_i32 s1, 8
	s_mul_hi_u32 s1, s11, s5
	s_mul_i32 s1, s1, s18
	s_cselect_b64 s[8:9], -1, 0
	s_sub_i32 s1, s11, s1
	s_sub_i32 s4, s1, s18
	s_cmp_ge_u32 s1, s18
	s_cselect_b32 s1, s4, s1
	s_sub_i32 s4, s1, s18
	v_writelane_b32 v252, s8, 41
	s_cmp_ge_u32 s1, s18
	s_cselect_b32 s1, s4, s1
	v_writelane_b32 v252, s9, 42
	v_writelane_b32 v252, s1, 43
	s_cmpk_lt_i32 s1, 0x80
	s_mul_hi_u32 s1, s12, s5
	s_mul_i32 s1, s1, s18
	s_cselect_b64 s[8:9], -1, 0
	s_sub_i32 s1, s12, s1
	s_sub_i32 s4, s1, s18
	s_cmp_ge_u32 s1, s18
	s_cselect_b32 s1, s4, s1
	s_sub_i32 s4, s1, s18
	v_writelane_b32 v252, s8, 44
	s_cmp_ge_u32 s1, s18
	s_cselect_b32 s1, s4, s1
	v_writelane_b32 v252, s9, 45
	v_writelane_b32 v252, s1, 46
	s_cmp_lt_i32 s1, 8
	s_mul_hi_u32 s1, s13, s5
	s_mul_i32 s1, s1, s18
	s_cselect_b64 s[8:9], -1, 0
	s_sub_i32 s1, s13, s1
	s_sub_i32 s4, s1, s18
	s_cmp_ge_u32 s1, s18
	s_cselect_b32 s1, s4, s1
	s_sub_i32 s4, s1, s18
	s_cmp_ge_u32 s1, s18
	v_writelane_b32 v252, s8, 47
	s_cselect_b32 s1, s4, s1
	s_cmpk_lt_i32 s1, 0x100
	v_writelane_b32 v252, s9, 48
	v_writelane_b32 v252, s1, 49
	s_cselect_b64 s[8:9], -1, 0
	v_writelane_b32 v252, s8, 50
	s_mul_hi_u32 s1, s14, s5
	s_cmpk_lt_i32 s6, 0x100
	v_writelane_b32 v252, s9, 51
	s_mul_i32 s1, s1, s18
	v_writelane_b32 v252, s6, 52
	s_cselect_b64 s[6:7], -1, 0
	s_sub_i32 s1, s14, s1
	s_sub_i32 s4, s1, s18
	s_cmp_ge_u32 s1, s18
	s_cselect_b32 s1, s4, s1
	s_sub_i32 s4, s1, s18
	s_cmp_ge_u32 s1, s18
	s_cselect_b32 s4, s4, s1
	v_writelane_b32 v252, s6, 53
	s_cmp_lt_i32 s4, 16
	s_mov_b32 s82, 0xf149f2ca
	v_writelane_b32 v252, s7, 54
	s_cselect_b64 s[6:7], -1, 0
	v_writelane_b32 v252, s6, 55
	s_movk_i32 s80, 0x2000
	s_movk_i32 s81, 0x3000
	v_writelane_b32 v252, s7, 56
	s_add_u32 s6, s48, 0x200
	v_writelane_b32 v252, s36, 57
	s_addc_u32 s7, s49, 0
	s_ashr_i32 s95, s94, 31
	v_writelane_b32 v253, s43, 0
	v_writelane_b32 v253, s44, 1
	v_writelane_b32 v253, s45, 2
	v_writelane_b32 v253, s46, 3
	v_writelane_b32 v253, s47, 4
	v_writelane_b32 v253, s48, 5
	v_writelane_b32 v253, s49, 6
	v_writelane_b32 v253, s50, 7
	v_writelane_b32 v253, s51, 8
	v_writelane_b32 v253, s6, 9
	s_lshl_b64 s[44:45], s[94:95], 11
	v_writelane_b32 v252, s37, 58
	v_writelane_b32 v253, s7, 10
	s_add_u32 s6, s54, 0xc00
	v_writelane_b32 v253, s52, 11
	s_addc_u32 s7, s55, 0
	s_sub_i32 s1, s19, s3
	v_writelane_b32 v253, s53, 12
	v_writelane_b32 v253, s54, 13
	v_writelane_b32 v253, s55, 14
	v_writelane_b32 v253, s56, 15
	v_writelane_b32 v253, s57, 16
	v_writelane_b32 v253, s58, 17
	v_writelane_b32 v253, s59, 18
	v_writelane_b32 v253, s60, 19
	v_writelane_b32 v253, s61, 20
	v_writelane_b32 v253, s62, 21
	v_writelane_b32 v253, s63, 22
	v_writelane_b32 v253, s64, 23
	v_writelane_b32 v253, s65, 24
	v_writelane_b32 v253, s66, 25
	v_writelane_b32 v253, s67, 26
	v_writelane_b32 v253, s6, 27
	s_sub_i32 s1, s1, s16
	s_addk_i32 s1, 0xfff
	v_writelane_b32 v253, s7, 28
	s_ashr_i32 s3, s2, 31
	v_writelane_b32 v253, s1, 29
	s_lshl_b64 s[2:3], s[2:3], 10
	s_lshl_b32 s1, s29, 8
	s_sub_i32 s5, s19, s18
	s_or_b32 s1, s2, s1
	s_add_u32 s2, s26, s1
	s_addc_u32 s3, s27, s3
	s_add_u32 s6, s2, 0x180000
	v_writelane_b32 v253, s2, 30
	s_addc_u32 s7, s3, 0
	v_readlane_b32 s52, v250, 18
	v_writelane_b32 v253, s3, 31
	v_writelane_b32 v253, s6, 32
	s_add_u32 s2, s26, 0x180000
	v_readlane_b32 s64, v250, 30
	v_writelane_b32 v253, s7, 33
	v_writelane_b32 v253, s20, 34
	s_addc_u32 s3, s27, 0
	s_sub_i32 s1, s19, s16
	v_writelane_b32 v253, s21, 35
	v_writelane_b32 v253, s22, 36
	v_writelane_b32 v253, s23, 37
	v_writelane_b32 v253, s24, 38
	v_writelane_b32 v253, s25, 39
	v_writelane_b32 v253, s26, 40
	v_writelane_b32 v253, s27, 41
	v_writelane_b32 v253, s2, 42
	s_addk_i32 s1, 0x103f
	v_readlane_b32 s65, v250, 31
	v_writelane_b32 v253, s3, 43
	s_mov_b32 s2, s16
	v_writelane_b32 v253, s2, 44
	v_readlane_b32 s62, v250, 28
	v_readlane_b32 s63, v250, 29
	v_writelane_b32 v253, s3, 45
	v_writelane_b32 v253, s19, 46
	v_writelane_b32 v253, s1, 47
	v_writelane_b32 v253, s5, 48
	s_add_i32 s1, s5, 64
	v_writelane_b32 v253, s1, 49
	s_or_b32 s1, s0, 0x50
	v_writelane_b32 v253, s1, 50
	s_or_b32 s0, s0, 4
	v_writelane_b32 v253, s0, 51
	s_add_u32 s0, s64, 0x7c00
	v_writelane_b32 v253, s0, 52
	s_addc_u32 s0, s65, 0
	v_writelane_b32 v253, s0, 53
	v_writelane_b32 v253, s4, 54
	s_lshl_b32 s0, s4, 5
	v_writelane_b32 v253, s0, 55
	v_writelane_b32 v253, s18, 56
	s_lshl_b32 s0, s18, 5
	v_writelane_b32 v253, s0, 57
	s_add_u32 s0, s62, 0x7c
	v_writelane_b32 v252, s38, 59
	v_writelane_b32 v253, s0, 58
	s_addc_u32 s0, s63, 0
	v_writelane_b32 v252, s39, 60
	v_writelane_b32 v253, s0, 59
	v_writelane_b32 v252, s40, 61
	v_writelane_b32 v253, s29, 60
	v_writelane_b32 v252, s41, 62
	v_writelane_b32 v253, s44, 61
	v_writelane_b32 v252, s42, 63
	s_movk_i32 s42, 0x100
	s_mov_b64 s[40:41], 0x10000
	s_movk_i32 s37, 0x80
	s_movk_i32 s43, 0xfff
	s_movk_i32 s46, 0x7fff
	s_mov_b32 s47, 0xfffffc0
	s_mov_b64 s[48:49], 0x8000
	s_movk_i32 s50, 0xd00
	s_mov_b32 s51, 0x8000
	s_movk_i32 s83, 0x1eff
	s_movk_i32 s95, 0x4000
	v_mbcnt_hi_u32_b32 v249, -1, v0
	v_writelane_b32 v253, s45, 62
	v_readlane_b32 s53, v250, 19
	v_readlane_b32 s54, v250, 20
	v_readlane_b32 s55, v250, 21
	v_readlane_b32 s56, v250, 22
	v_readlane_b32 s57, v250, 23
	v_readlane_b32 s58, v250, 24
	v_readlane_b32 s59, v250, 25
	v_readlane_b32 s60, v250, 26
	v_readlane_b32 s61, v250, 27
	v_readlane_b32 s66, v250, 32
	v_readlane_b32 s67, v250, 33
	s_branch .LBB0_5

; #define MFMA32(a, b, c) __builtin_amdgcn_mfma_f32_32x32x16_bf16((a), (b), (c), 0, 0, 0)
; DI void phaseB2(const Params& p, int bh, char* smem, int n_begin, int n_end) {
;     ...
;   for (int n = n_begin; n < n_end; ++n) {
;     B2_LOAD(n + 1 < 32 ? n + 1 : n);
;     f32x16 vn[2], o[2];
; #pragma unroll
;     for (int it = 0; it < 2; ++it) {
;       f32x16 aw;
; #pragma unroll
;       for (int e = 0; e < 16; ++e) aw[e] = 0.f;
; #pragma unroll
;       for (int T = 0; T < 4; ++T)
; #pragma unroll
;         for (int s = 0; s < 2; ++s) aw = MFMA32(ld16(wg + (it * 4096 + (T * 2 + s) * 512) + lo8), pack8(S[T], s), aw);
; #pragma unroll
;       for (int g = 0; g < 4; ++g) {
;         const uint2 uu = it == 0 ? (g == 0 ? pu0 : g == 1 ? pu1 : g == 2 ? pu2 : pu3) : (g == 0 ? pu4 : g == 1 ? pu5 : g == 2 ? pu6 : pu7);
;         vn[it][4 * g + 0] = __uint_as_float(uu.x << 16) - aw[4 * g + 0];
;         vn[it][4 * g + 1] = __uint_as_float(uu.x & 0xffff0000u) - aw[4 * g + 1];
;         vn[it][4 * g + 2] = __uint_as_float(uu.y << 16) - aw[4 * g + 2];
;         vn[it][4 * g + 3] = __uint_as_float(uu.y & 0xffff0000u) - aw[4 * g + 3];
;       }
;     }
.LBB0_1770:
	s_ashr_i32 s3, s2, 31
	s_lshl_b64 s[4:5], s[2:3], 14
	v_lshl_add_u64 v[66:67], v[208:209], 0, s[4:5]
	v_add_co_u32_e32 v74, vcc, s80, v66
	global_load_dwordx4 v[98:101], v[66:67], off
	s_nop 0
	v_addc_co_u32_e32 v75, vcc, 0, v67, vcc
	v_add_co_u32_e32 v66, vcc, s81, v66
	v_lshl_add_u64 v[68:69], v[210:211], 0, s[4:5]
	s_nop 0
	v_addc_co_u32_e32 v67, vcc, 0, v67, vcc
	global_load_dwordx4 v[102:105], v[74:75], off offset:-4096
	global_load_dwordx4 v[106:109], v[74:75], off
	global_load_dwordx4 v[110:113], v[66:67], off
	global_load_dwordx4 v[114:117], v[68:69], off
	v_add_co_u32_e32 v66, vcc, s80, v68
	v_lshl_add_u64 v[70:71], v[212:213], 0, s[4:5]
	s_nop 0
	v_addc_co_u32_e32 v67, vcc, 0, v69, vcc
	global_load_dwordx4 v[118:121], v[66:67], off offset:-4096
	global_load_dwordx4 v[122:125], v[66:67], off
	v_add_co_u32_e32 v66, vcc, s81, v68
	s_lshl_b64 s[6:7], s[2:3], 13
	s_nop 0
	v_addc_co_u32_e32 v67, vcc, 0, v69, vcc
	global_load_dwordx4 v[126:129], v[66:67], off
	global_load_dwordx4 v[130:133], v[70:71], off
	v_add_co_u32_e32 v66, vcc, s80, v70
	v_lshl_add_u64 v[72:73], v[214:215], 0, s[6:7]
	s_nop 0
	v_addc_co_u32_e32 v67, vcc, 0, v71, vcc
	global_load_dwordx4 v[134:137], v[66:67], off offset:-4096
	global_load_dwordx4 v[138:141], v[66:67], off
	v_add_co_u32_e32 v66, vcc, s81, v70
	v_cvt_pk_bf16_f32 v82, v2, v3
	s_nop 0
	v_addc_co_u32_e32 v67, vcc, 0, v71, vcc
	global_load_dwordx4 v[142:145], v[66:67], off
	global_load_dwordx4 v[146:149], v[72:73], off
	v_add_co_u32_e32 v66, vcc, s97, v72
	v_cvt_pk_bf16_f32 v83, v4, v5
	s_nop 0
	v_addc_co_u32_e32 v67, vcc, 0, v73, vcc
	global_load_dwordx4 v[150:153], v[66:67], off
	ds_read_b128 v[66:69], v240
	ds_read_b128 v[86:89], v240 offset:1024
	v_cvt_pk_bf16_f32 v84, v6, v7
	v_cvt_pk_bf16_f32 v85, v8, v9
	v_cvt_pk_bf16_f32 v194, v10, v11
	v_cvt_pk_bf16_f32 v195, v12, v13
	s_waitcnt lgkmcnt(1)
	v_mfma_f32_32x32x16_bf16 v[66:81], v[66:69], v[82:85], 0
	v_cvt_pk_bf16_f32 v196, v14, v15
	v_cvt_pk_bf16_f32 v197, v16, v17
	v_cvt_pk_bf16_f32 v190, v50, v51
	v_cvt_pk_bf16_f32 v191, v52, v53
	v_cvt_pk_bf16_f32 v192, v54, v55
	v_cvt_pk_bf16_f32 v193, v56, v57
	v_cvt_pk_bf16_f32 v186, v58, v59
	s_waitcnt lgkmcnt(0)
	v_mfma_f32_32x32x16_bf16 v[66:81], v[86:89], v[194:197], v[66:81]
	ds_read_b128 v[86:89], v240 offset:2048
	v_cvt_pk_bf16_f32 v187, v60, v61
	v_cvt_pk_bf16_f32 v188, v62, v63
	v_cvt_pk_bf16_f32 v189, v64, v65
	v_cvt_pk_bf16_f32 v182, v34, v35
	v_cvt_pk_bf16_f32 v183, v36, v37
	v_cvt_pk_bf16_f32 v184, v38, v39
	s_waitcnt lgkmcnt(0)
	v_mfma_f32_32x32x16_bf16 v[66:81], v[86:89], v[190:193], v[66:81]
	ds_read_b128 v[86:89], v240 offset:3072
	v_cvt_pk_bf16_f32 v185, v40, v41
	v_cvt_pk_bf16_f32 v178, v42, v43
	v_cvt_pk_bf16_f32 v179, v44, v45
	v_cvt_pk_bf16_f32 v180, v46, v47
	v_cvt_pk_bf16_f32 v181, v48, v49
	v_cvt_pk_bf16_f32 v174, v18, v19
	s_waitcnt lgkmcnt(0)
	v_mfma_f32_32x32x16_bf16 v[66:81], v[86:89], v[186:189], v[66:81]
	ds_read_b128 v[86:89], v240 offset:4096
	v_cvt_pk_bf16_f32 v175, v20, v21
	v_cvt_pk_bf16_f32 v176, v22, v23
	v_cvt_pk_bf16_f32 v177, v24, v25
	v_cvt_pk_bf16_f32 v170, v26, v27
	v_cvt_pk_bf16_f32 v171, v28, v29
	v_cvt_pk_bf16_f32 v172, v30, v31
	s_waitcnt lgkmcnt(0)
	v_mfma_f32_32x32x16_bf16 v[66:81], v[86:89], v[182:185], v[66:81]
	ds_read_b128 v[86:89], v240 offset:5120
	v_cvt_pk_bf16_f32 v173, v32, v33
	s_waitcnt vmcnt(21)
	v_lshlrev_b32_e32 v0, 16, v226
	s_waitcnt lgkmcnt(0)
	v_mfma_f32_32x32x16_bf16 v[66:81], v[86:89], v[178:181], v[66:81]
	ds_read_b128 v[86:89], v240 offset:6144
	s_waitcnt lgkmcnt(0)
	v_mfma_f32_32x32x16_bf16 v[66:81], v[86:89], v[174:177], v[66:81]
	ds_read_b128 v[86:89], v240 offset:7168
	s_waitcnt lgkmcnt(0)
	v_mfma_f32_32x32x16_bf16 v[66:81], v[86:89], v[170:173], v[66:81]
	ds_read_b128 v[86:89], v240 offset:9216
	s_nop 10
	v_sub_f32_e32 v0, v0, v66
	v_and_b32_e32 v66, 0xffff0000, v226
	v_sub_f32_e32 v90, v66, v67
	v_lshlrev_b32_e32 v66, 16, v227
	v_sub_f32_e32 v91, v66, v68
	v_and_b32_e32 v66, 0xffff0000, v227
	v_sub_f32_e32 v92, v66, v69
	s_waitcnt vmcnt(20)
	v_lshlrev_b32_e32 v66, 16, v224
	v_sub_f32_e32 v93, v66, v70
	v_and_b32_e32 v66, 0xffff0000, v224
	v_sub_f32_e32 v94, v66, v71
	v_lshlrev_b32_e32 v66, 16, v225
	v_sub_f32_e32 v95, v66, v72
	v_and_b32_e32 v66, 0xffff0000, v225
	v_sub_f32_e32 v96, v66, v73
	s_waitcnt vmcnt(19)
	v_lshlrev_b32_e32 v66, 16, v222
	v_sub_f32_e32 v97, v66, v74
	v_and_b32_e32 v66, 0xffff0000, v222
	v_sub_f32_e32 v154, v66, v75
	v_lshlrev_b32_e32 v66, 16, v223
	v_sub_f32_e32 v155, v66, v76
	v_and_b32_e32 v66, 0xffff0000, v223
	v_sub_f32_e32 v156, v66, v77
	s_waitcnt vmcnt(18)
	v_lshlrev_b32_e32 v66, 16, v220
	v_sub_f32_e32 v157, v66, v78
	v_and_b32_e32 v66, 0xffff0000, v220
	v_sub_f32_e32 v158, v66, v79
	v_lshlrev_b32_e32 v66, 16, v221
	v_sub_f32_e32 v159, v66, v80
	v_and_b32_e32 v66, 0xffff0000, v221
	v_sub_f32_e32 v160, v66, v81
	ds_read_b128 v[66:69], v240 offset:8192
	s_waitcnt lgkmcnt(0)
	v_mfma_f32_32x32x16_bf16 v[66:81], v[66:69], v[82:85], 0
	v_cvt_pk_bf16_f32 v164, v157, v158
	v_cvt_pk_bf16_f32 v165, v159, v160
	v_cvt_pk_bf16_f32 v162, v97, v154
	v_cvt_pk_bf16_f32 v163, v155, v156
	v_cvt_pk_bf16_f32 v166, v0, v90
	v_cvt_pk_bf16_f32 v167, v91, v92
	v_cvt_pk_bf16_f32 v168, v93, v94
	v_mfma_f32_32x32x16_bf16 v[66:81], v[86:89], v[194:197], v[66:81]
	ds_read_b128 v[86:89], v240 offset:10240
	v_cvt_pk_bf16_f32 v169, v95, v96
	ds_bpermute_b32 v0, v241, v228
	v_add_u32_e32 v241, 4, v241
	s_waitcnt lgkmcnt(0)
; #define MFMA32(a, b, c) __builtin_amdgcn_mfma_f32_32x32x16_bf16((a), (b), (c), 0, 0, 0)
; DI void phaseB2(const Params& p, int bh, char* smem, int n_begin, int n_end) {
;     ...
;       for (int g = 0; g < 4; ++g) {
;         const uint2 uu = it == 0 ? (g == 0 ? pu0 : g == 1 ? pu1 : g == 2 ? pu2 : pu3) : (g == 0 ? pu4 : g == 1 ? pu5 : g == 2 ? pu6 : pu7);
;         vn[it][4 * g + 0] = __uint_as_float(uu.x << 16) - aw[4 * g + 0];
;         vn[it][4 * g + 1] = __uint_as_float(uu.x & 0xffff0000u) - aw[4 * g + 1];
;         vn[it][4 * g + 2] = __uint_as_float(uu.y << 16) - aw[4 * g + 2];
;         vn[it][4 * g + 3] = __uint_as_float(uu.y & 0xffff0000u) - aw[4 * g + 3];
;       }
;     }
;     B2_LOADU(n + 1 < 32 ? n + 1 : n);
;     bf16x8 Vb[2][2];
; #pragma unroll
;     for (int jt = 0; jt < 2; ++jt) { Vb[jt][0] = pack8(vn[jt], 0); Vb[jt][1] = pack8(vn[jt], 1); }
; #pragma unroll
;     for (int it = 0; it < 2; ++it) {
; #pragma unroll
;       for (int e = 0; e < 16; ++e) o[it][e] = 0.f;
; #pragma unroll
;       for (int T = 0; T < 4; ++T)
; #pragma unroll
;         for (int s = 0; s < 2; ++s) o[it] = MFMA32(ld16(qg + (it * 4096 + (T * 2 + s) * 512) + lo8), pack8(S[T], s), o[it]);
; #pragma unroll
;       for (int jt = 0; jt < 2; ++jt)
; #pragma unroll
;         for (int s = 0; s < 2; ++s)
;           o[it] = MFMA32(ld16(ag + (it * 2048 + (jt * 2 + s) * 512) + lo8), Vb[jt][s], o[it]);
;     }
;     const float egl = __shfl(eglv, n);
; #pragma unroll
;     for (int T = 0; T < 4; ++T) {
;       f32x16 acc;
; #pragma unroll
;       for (int e = 0; e < 16; ++e) acc[e] = S[T][e] * egl;
; #pragma unroll
;       for (int jt = 0; jt < 2; ++jt)
; #pragma unroll
;         for (int s = 0; s < 2; ++s)
;           acc = MFMA32(ld16(kg + (T * 2048 + (jt * 2 + s) * 512) + lo8), Vb[jt][s], acc);
	v_pk_mul_f32 v[16:17], v[16:17], v[0:1] op_sel_hi:[1,0]
	v_mfma_f32_32x32x16_bf16 v[66:81], v[86:89], v[190:193], v[66:81]
	ds_read_b128 v[86:89], v240 offset:11264
	v_mul_f32_e64 v14, v14, v0
	v_mul_f32_e64 v15, v15, v0
	v_mul_f32_e64 v12, v12, v0
	v_mul_f32_e64 v13, v13, v0
	v_pk_mul_f32 v[10:11], v[10:11], v[0:1] op_sel_hi:[1,0]
	v_pk_mul_f32 v[8:9], v[8:9], v[0:1] op_sel_hi:[1,0]
	v_pk_mul_f32 v[6:7], v[6:7], v[0:1] op_sel_hi:[1,0]
	v_pk_mul_f32 v[4:5], v[4:5], v[0:1] op_sel_hi:[1,0]
	s_waitcnt lgkmcnt(0)
	v_mfma_f32_32x32x16_bf16 v[66:81], v[86:89], v[186:189], v[66:81]
	ds_read_b128 v[86:89], v240 offset:12288
	v_mul_f32_e64 v2, v2, v0
	v_mul_f32_e64 v3, v3, v0
	v_mul_f32_e64 v64, v64, v0
	v_mul_f32_e64 v65, v65, v0
	v_pk_mul_f32 v[62:63], v[62:63], v[0:1] op_sel_hi:[1,0]
	v_pk_mul_f32 v[60:61], v[60:61], v[0:1] op_sel_hi:[1,0]
	v_pk_mul_f32 v[58:59], v[58:59], v[0:1] op_sel_hi:[1,0]
	v_pk_mul_f32 v[56:57], v[56:57], v[0:1] op_sel_hi:[1,0]
	s_waitcnt lgkmcnt(0)
	v_mfma_f32_32x32x16_bf16 v[66:81], v[86:89], v[182:185], v[66:81]
	ds_read_b128 v[86:89], v240 offset:13312
	v_mul_f32_e64 v54, v54, v0
	v_mul_f32_e64 v55, v55, v0
	v_mul_f32_e64 v52, v52, v0
	v_mul_f32_e64 v53, v53, v0
	v_pk_mul_f32 v[50:51], v[50:51], v[0:1] op_sel_hi:[1,0]
	v_pk_mul_f32 v[48:49], v[48:49], v[0:1] op_sel_hi:[1,0]
	v_pk_mul_f32 v[46:47], v[46:47], v[0:1] op_sel_hi:[1,0]
	v_pk_mul_f32 v[44:45], v[44:45], v[0:1] op_sel_hi:[1,0]
	s_waitcnt lgkmcnt(0)
	v_mfma_f32_32x32x16_bf16 v[66:81], v[86:89], v[178:181], v[66:81]
	ds_read_b128 v[86:89], v240 offset:14336
	v_mul_f32_e64 v42, v42, v0
	v_mul_f32_e64 v43, v43, v0
	v_mul_f32_e64 v40, v40, v0
	v_mul_f32_e64 v41, v41, v0
	v_pk_mul_f32 v[38:39], v[38:39], v[0:1] op_sel_hi:[1,0]
	v_pk_mul_f32 v[36:37], v[36:37], v[0:1] op_sel_hi:[1,0]
	v_pk_mul_f32 v[34:35], v[34:35], v[0:1] op_sel_hi:[1,0]
	v_pk_mul_f32 v[32:33], v[32:33], v[0:1] op_sel_hi:[1,0]
	s_waitcnt lgkmcnt(0)
	v_mfma_f32_32x32x16_bf16 v[66:81], v[86:89], v[174:177], v[66:81]
	ds_read_b128 v[86:89], v240 offset:15360
	v_mul_f32_e64 v30, v30, v0
	v_mul_f32_e64 v31, v31, v0
	v_mul_f32_e64 v28, v28, v0
	v_mul_f32_e64 v29, v29, v0
	v_pk_mul_f32 v[26:27], v[26:27], v[0:1] op_sel_hi:[1,0]
	v_pk_mul_f32 v[24:25], v[24:25], v[0:1] op_sel_hi:[1,0]
	v_pk_mul_f32 v[22:23], v[22:23], v[0:1] op_sel_hi:[1,0]
	v_pk_mul_f32 v[20:21], v[20:21], v[0:1] op_sel_hi:[1,0]
	s_waitcnt lgkmcnt(0)
	v_mfma_f32_32x32x16_bf16 v[66:81], v[86:89], v[170:173], v[66:81]
	s_waitcnt vmcnt(17)
	v_lshlrev_b32_e32 v86, 16, v206
	v_and_b32_e32 v87, 0xffff0000, v206
	v_mul_f32_e64 v18, v18, v0
	v_mul_f32_e64 v19, v19, v0
	s_nop 6
	v_pk_add_f32 v[66:67], v[86:87], v[66:67] neg_lo:[0,1] neg_hi:[0,1]
	v_lshlrev_b32_e32 v86, 16, v207
	v_and_b32_e32 v87, 0xffff0000, v207
	v_pk_add_f32 v[68:69], v[86:87], v[68:69] neg_lo:[0,1] neg_hi:[0,1]
	s_waitcnt vmcnt(16)
	v_lshlrev_b32_e32 v86, 16, v204
	v_and_b32_e32 v87, 0xffff0000, v204
	v_pk_add_f32 v[70:71], v[86:87], v[70:71] neg_lo:[0,1] neg_hi:[0,1]
	v_lshlrev_b32_e32 v86, 16, v205
	v_and_b32_e32 v87, 0xffff0000, v205
	v_pk_add_f32 v[72:73], v[86:87], v[72:73] neg_lo:[0,1] neg_hi:[0,1]
	s_waitcnt vmcnt(15)
	v_lshlrev_b32_e32 v86, 16, v202
	v_and_b32_e32 v87, 0xffff0000, v202
	v_pk_add_f32 v[74:75], v[86:87], v[74:75] neg_lo:[0,1] neg_hi:[0,1]
	v_lshlrev_b32_e32 v86, 16, v203
	v_and_b32_e32 v87, 0xffff0000, v203
	v_pk_add_f32 v[76:77], v[86:87], v[76:77] neg_lo:[0,1] neg_hi:[0,1]
	s_waitcnt vmcnt(14)
	v_lshlrev_b32_e32 v86, 16, v200
	v_and_b32_e32 v87, 0xffff0000, v200
	v_pk_add_f32 v[78:79], v[86:87], v[78:79] neg_lo:[0,1] neg_hi:[0,1]
	v_lshlrev_b32_e32 v86, 16, v201
	v_and_b32_e32 v87, 0xffff0000, v201
	v_pk_add_f32 v[80:81], v[86:87], v[80:81] neg_lo:[0,1] neg_hi:[0,1]
	v_lshl_add_u64 v[86:87], v[216:217], 0, s[4:5]
	global_load_dwordx2 v[226:227], v[86:87], off
	global_load_dwordx2 v[224:225], v[86:87], off offset:512
	global_load_dwordx2 v[222:223], v[86:87], off offset:1024
	global_load_dwordx2 v[220:221], v[86:87], off offset:1536
	global_load_dwordx2 v[206:207], v[86:87], off offset:2048
	global_load_dwordx2 v[204:205], v[86:87], off offset:2560
	global_load_dwordx2 v[202:203], v[86:87], off offset:3072
	global_load_dwordx2 v[200:201], v[86:87], off offset:3584
	v_cvt_pk_bf16_f32 v158, v66, v67
	v_cvt_pk_bf16_f32 v159, v68, v69
	ds_read_b128 v[66:69], v240 offset:16384
	ds_read_b128 v[86:89], v240 offset:17408
	v_cvt_pk_bf16_f32 v160, v70, v71
	v_cvt_pk_bf16_f32 v161, v72, v73
	v_cvt_pk_bf16_f32 v154, v74, v75
	v_cvt_pk_bf16_f32 v155, v76, v77
	v_cvt_pk_bf16_f32 v156, v78, v79
	v_cvt_pk_bf16_f32 v157, v80, v81
	s_waitcnt lgkmcnt(1)
	v_mfma_f32_32x32x16_bf16 v[66:81], v[66:69], v[82:85], 0
	ds_read_b128 v[242:245], v240 offset:25600
	s_waitcnt lgkmcnt(1)
	v_mfma_f32_32x32x16_bf16 v[66:81], v[86:89], v[194:197], v[66:81]
	ds_read_b128 v[86:89], v240 offset:18432
	s_waitcnt lgkmcnt(0)
	v_mfma_f32_32x32x16_bf16 v[66:81], v[86:89], v[190:193], v[66:81]
	ds_read_b128 v[86:89], v240 offset:19456
	s_waitcnt lgkmcnt(0)
	v_mfma_f32_32x32x16_bf16 v[66:81], v[86:89], v[186:189], v[66:81]
	ds_read_b128 v[86:89], v240 offset:20480
	s_waitcnt lgkmcnt(0)
	v_mfma_f32_32x32x16_bf16 v[66:81], v[86:89], v[182:185], v[66:81]
	ds_read_b128 v[86:89], v240 offset:21504
	s_waitcnt lgkmcnt(0)
	v_mfma_f32_32x32x16_bf16 v[66:81], v[86:89], v[178:181], v[66:81]
	ds_read_b128 v[86:89], v240 offset:22528
	s_waitcnt lgkmcnt(0)
	v_mfma_f32_32x32x16_bf16 v[66:81], v[86:89], v[174:177], v[66:81]
	ds_read_b128 v[86:89], v240 offset:23552
	s_waitcnt lgkmcnt(0)
	v_mfma_f32_32x32x16_bf16 v[66:81], v[86:89], v[170:173], v[66:81]
	ds_read_b128 v[86:89], v240 offset:49152
	s_waitcnt lgkmcnt(0)
; #define MFMA32(a, b, c) __builtin_amdgcn_mfma_f32_32x32x16_bf16((a), (b), (c), 0, 0, 0)
; #define B2_STORE() do { uint4* l_ = (uint4*)L + tid; \
;     l_[0] = pw0; l_[256] = pw1; l_[512] = pw2; l_[768] = pw3; l_[1024] = pq0; l_[1280] = pq1; l_[1536] = pq2; l_[1792] = pq3; \
;     l_[2048] = pk0; l_[2304] = pk1; l_[2560] = pk2; l_[2816] = pk3; l_[3072] = pa0; l_[3328] = pa1; } while (0)
; DI void phaseB2(const Params& p, int bh, char* smem, int n_begin, int n_end) {
;     ...
;     for (int it = 0; it < 2; ++it) {
; #pragma unroll
;       for (int e = 0; e < 16; ++e) o[it][e] = 0.f;
; #pragma unroll
;       for (int T = 0; T < 4; ++T)
; #pragma unroll
;         for (int s = 0; s < 2; ++s) o[it] = MFMA32(ld16(qg + (it * 4096 + (T * 2 + s) * 512) + lo8), pack8(S[T], s), o[it]);
; #pragma unroll
;       for (int jt = 0; jt < 2; ++jt)
; #pragma unroll
;         for (int s = 0; s < 2; ++s)
;           o[it] = MFMA32(ld16(ag + (it * 2048 + (jt * 2 + s) * 512) + lo8), Vb[jt][s], o[it]);
;     }
;     const float egl = __shfl(eglv, n);
; #pragma unroll
;     for (int T = 0; T < 4; ++T) {
;       f32x16 acc;
; #pragma unroll
;       for (int e = 0; e < 16; ++e) acc[e] = S[T][e] * egl;
; #pragma unroll
;       for (int jt = 0; jt < 2; ++jt)
; #pragma unroll
;         for (int s = 0; s < 2; ++s)
;           acc = MFMA32(ld16(kg + (T * 2048 + (jt * 2 + s) * 512) + lo8), Vb[jt][s], acc);
;       S[T] = acc;
;     }
;     asm volatile("s_waitcnt lgkmcnt(0)\n\ts_barrier" ::: "memory");
;     B2_STORE();
;     asm volatile("s_waitcnt lgkmcnt(0)\n\ts_barrier" ::: "memory");
	v_mfma_f32_32x32x16_bf16 v[66:81], v[86:89], v[166:169], v[66:81]
	ds_read_b128 v[86:89], v240 offset:50176
	s_waitcnt lgkmcnt(0)
	v_mfma_f32_32x32x16_bf16 v[66:81], v[86:89], v[162:165], v[66:81]
	ds_read_b128 v[86:89], v240 offset:51200
	s_waitcnt lgkmcnt(0)
	v_mfma_f32_32x32x16_bf16 v[66:81], v[86:89], v[158:161], v[66:81]
	ds_read_b128 v[86:89], v240 offset:52224
	s_waitcnt lgkmcnt(0)
	v_mfma_f32_32x32x16_bf16 v[66:81], v[86:89], v[154:157], v[66:81]
	ds_read_b128 v[86:89], v240 offset:24576
	s_waitcnt lgkmcnt(0)
	v_mfma_f32_32x32x16_bf16 v[82:97], v[86:89], v[82:85], 0
	s_nop 8
	v_cvt_pk_bf16_f32 v0, v66, s0
	v_mfma_f32_32x32x16_bf16 v[82:97], v[242:245], v[194:197], v[82:97]
	ds_read_b128 v[194:197], v240 offset:26624
	s_waitcnt lgkmcnt(0)
	v_mfma_f32_32x32x16_bf16 v[82:97], v[194:197], v[190:193], v[82:97]
	ds_read_b128 v[190:193], v240 offset:27648
	s_waitcnt lgkmcnt(0)
	v_mfma_f32_32x32x16_bf16 v[82:97], v[190:193], v[186:189], v[82:97]
	ds_read_b128 v[186:189], v240 offset:28672
	s_waitcnt lgkmcnt(0)
	v_mfma_f32_32x32x16_bf16 v[82:97], v[186:189], v[182:185], v[82:97]
	ds_read_b128 v[182:185], v240 offset:29696
	s_waitcnt lgkmcnt(0)
	v_mfma_f32_32x32x16_bf16 v[82:97], v[182:185], v[178:181], v[82:97]
	ds_read_b128 v[178:181], v240 offset:30720
	s_waitcnt lgkmcnt(0)
	v_mfma_f32_32x32x16_bf16 v[82:97], v[178:181], v[174:177], v[82:97]
	ds_read_b128 v[174:177], v240 offset:31744
	s_waitcnt lgkmcnt(0)
	v_mfma_f32_32x32x16_bf16 v[82:97], v[174:177], v[170:173], v[82:97]
	ds_read_b128 v[170:173], v240 offset:53248
	s_waitcnt lgkmcnt(0)
	v_mfma_f32_32x32x16_bf16 v[82:97], v[170:173], v[166:169], v[82:97]
	ds_read_b128 v[170:173], v240 offset:54272
	s_waitcnt lgkmcnt(0)
	v_mfma_f32_32x32x16_bf16 v[82:97], v[170:173], v[162:165], v[82:97]
	ds_read_b128 v[170:173], v240 offset:55296
	s_waitcnt lgkmcnt(0)
	v_mfma_f32_32x32x16_bf16 v[82:97], v[170:173], v[158:161], v[82:97]
	ds_read_b128 v[170:173], v240 offset:56320
	s_waitcnt lgkmcnt(0)
	v_mfma_f32_32x32x16_bf16 v[82:97], v[170:173], v[154:157], v[82:97]
	ds_read_b128 v[170:173], v240 offset:32768
	s_waitcnt lgkmcnt(0)
	v_mfma_f32_32x32x16_bf16 v[2:17], v[170:173], v[166:169], v[2:17]
	ds_read_b128 v[170:173], v240 offset:33792
	s_waitcnt lgkmcnt(0)
	v_mfma_f32_32x32x16_bf16 v[2:17], v[170:173], v[162:165], v[2:17]
	ds_read_b128 v[170:173], v240 offset:34816
	s_waitcnt lgkmcnt(0)
	v_mfma_f32_32x32x16_bf16 v[2:17], v[170:173], v[158:161], v[2:17]
	ds_read_b128 v[170:173], v240 offset:35840
	s_waitcnt lgkmcnt(0)
	v_mfma_f32_32x32x16_bf16 v[2:17], v[170:173], v[154:157], v[2:17]
	ds_read_b128 v[170:173], v240 offset:36864
	s_waitcnt lgkmcnt(0)
	v_mfma_f32_32x32x16_bf16 v[50:65], v[170:173], v[166:169], v[50:65]
	ds_read_b128 v[170:173], v240 offset:37888
	s_waitcnt lgkmcnt(0)
	v_mfma_f32_32x32x16_bf16 v[50:65], v[170:173], v[162:165], v[50:65]
	ds_read_b128 v[170:173], v240 offset:38912
	s_waitcnt lgkmcnt(0)
	v_mfma_f32_32x32x16_bf16 v[50:65], v[170:173], v[158:161], v[50:65]
	ds_read_b128 v[170:173], v240 offset:39936
	s_waitcnt lgkmcnt(0)
	v_mfma_f32_32x32x16_bf16 v[50:65], v[170:173], v[154:157], v[50:65]
	ds_read_b128 v[170:173], v240 offset:40960
	s_waitcnt lgkmcnt(0)
	v_mfma_f32_32x32x16_bf16 v[34:49], v[170:173], v[166:169], v[34:49]
	ds_read_b128 v[170:173], v240 offset:41984
	s_waitcnt lgkmcnt(0)
	v_mfma_f32_32x32x16_bf16 v[34:49], v[170:173], v[162:165], v[34:49]
	ds_read_b128 v[170:173], v240 offset:43008
	s_waitcnt lgkmcnt(0)
	v_mfma_f32_32x32x16_bf16 v[34:49], v[170:173], v[158:161], v[34:49]
	ds_read_b128 v[170:173], v240 offset:44032
	s_waitcnt lgkmcnt(0)
	v_mfma_f32_32x32x16_bf16 v[34:49], v[170:173], v[154:157], v[34:49]
	ds_read_b128 v[170:173], v240 offset:45056
	s_waitcnt lgkmcnt(0)
	v_mfma_f32_32x32x16_bf16 v[18:33], v[170:173], v[166:169], v[18:33]
	ds_read_b128 v[166:169], v240 offset:46080
	s_waitcnt lgkmcnt(0)
	v_mfma_f32_32x32x16_bf16 v[18:33], v[166:169], v[162:165], v[18:33]
	ds_read_b128 v[162:165], v240 offset:47104
	s_waitcnt lgkmcnt(0)
	v_mfma_f32_32x32x16_bf16 v[18:33], v[162:165], v[158:161], v[18:33]
	ds_read_b128 v[158:161], v240 offset:48128
	s_waitcnt lgkmcnt(0)
	s_barrier
	s_waitcnt vmcnt(21)
	ds_write_b128 v229, v[98:101]
	s_waitcnt vmcnt(20)
	ds_write_b128 v229, v[102:105] offset:4096
	s_waitcnt vmcnt(19)
	ds_write_b128 v229, v[106:109] offset:8192
	s_waitcnt vmcnt(18)
	ds_write_b128 v229, v[110:113] offset:12288
	s_waitcnt vmcnt(17)
	ds_write_b128 v229, v[114:117] offset:16384
	s_waitcnt vmcnt(16)
	ds_write_b128 v229, v[118:121] offset:20480
	s_waitcnt vmcnt(15)
	ds_write_b128 v229, v[122:125] offset:24576
	s_waitcnt vmcnt(14)
	ds_write_b128 v229, v[126:129] offset:28672
	s_waitcnt vmcnt(13)
	ds_write_b128 v229, v[130:133] offset:32768
	s_waitcnt vmcnt(12)
	ds_write_b128 v229, v[134:137] offset:36864
	s_waitcnt vmcnt(11)
	ds_write_b128 v229, v[138:141] offset:40960
	s_waitcnt vmcnt(10)
	ds_write_b128 v229, v[142:145] offset:45056
	s_waitcnt vmcnt(9)
	ds_write_b128 v229, v[146:149] offset:49152
	s_waitcnt vmcnt(8)
	ds_write_b128 v229, v[150:153] offset:53248
	v_lshl_add_u64 v[98:99], v[218:219], 0, s[0:1]
	s_waitcnt lgkmcnt(0)
	s_barrier
; DI bf16_t f2bf(float x) { return (bf16_t)(pack2(x, 0.f) & 0xffffu); }
; DI int crow(int reg, int hh) { return (reg & 3) + 8 * (reg >> 2) + 4 * hh; }
; DI void phaseB2(const Params& p, int bh, char* smem, int n_begin, int n_end) {
;     ...
;       bf16_t* og = p.ob + (size_t)(b * SEQ + n * 64) * 512 + hd * 128 + v0 + r;
; #pragma unroll
;       for (int it = 0; it < 2; ++it)
; #pragma unroll
;         for (int e = 0; e < 16; ++e) og[(size_t)(it * 32 + crow(e, hh)) * 512] = f2bf(o[it][e]);
;     }
;   }
;   if (n_end < 32) {
; #pragma unroll
;     for (int T = 0; T < 4; ++T)
; #pragma unroll
;       for (int q4 = 0; q4 < 4; ++q4)
;         *(float4*)(sst + T * 16 + q4 * 4) = make_float4(S[T][q4 * 4], S[T][q4 * 4 + 1], S[T][q4 * 4 + 2], S[T][q4 * 4 + 3]);
;   }
;   __syncthreads();
	global_store_short v[98:99], v0, off
	v_cvt_pk_bf16_f32 v0, v67, s0
	global_store_short v[98:99], v0, off offset:1024
	v_cvt_pk_bf16_f32 v0, v68, s0
	global_store_short v[98:99], v0, off offset:2048
	v_cvt_pk_bf16_f32 v0, v69, s0
	v_add_co_u32_e32 v66, vcc, s80, v98
	global_store_short v[98:99], v0, off offset:3072
	v_cvt_pk_bf16_f32 v0, v70, s0
	v_addc_co_u32_e32 v67, vcc, 0, v99, vcc
	global_store_short v[66:67], v0, off
	v_cvt_pk_bf16_f32 v0, v71, s0
	global_store_short v[66:67], v0, off offset:1024
	v_cvt_pk_bf16_f32 v0, v72, s0
	global_store_short v[66:67], v0, off offset:2048
	v_cvt_pk_bf16_f32 v0, v73, s0
	global_store_short v[66:67], v0, off offset:3072
	v_add_co_u32_e32 v66, vcc, s95, v98
	v_cvt_pk_bf16_f32 v0, v74, s0
	s_nop 0
	v_addc_co_u32_e32 v67, vcc, 0, v99, vcc
	global_store_short v[66:67], v0, off
	v_cvt_pk_bf16_f32 v0, v75, s0
	global_store_short v[66:67], v0, off offset:1024
	v_cvt_pk_bf16_f32 v0, v76, s0
	global_store_short v[66:67], v0, off offset:2048
	v_cvt_pk_bf16_f32 v0, v77, s0
	global_store_short v[66:67], v0, off offset:3072
	v_add_co_u32_e32 v66, vcc, s8, v98
	v_cvt_pk_bf16_f32 v0, v78, s0
	s_nop 0
	v_addc_co_u32_e32 v67, vcc, 0, v99, vcc
	global_store_short v[66:67], v0, off
	v_cvt_pk_bf16_f32 v0, v79, s0
	global_store_short v[66:67], v0, off offset:1024
	v_cvt_pk_bf16_f32 v0, v80, s0
	global_store_short v[66:67], v0, off offset:2048
	v_cvt_pk_bf16_f32 v0, v81, s0
	global_store_short v[66:67], v0, off offset:3072
	v_add_co_u32_e32 v66, vcc, s51, v98
	v_cvt_pk_bf16_f32 v0, v82, s0
	s_nop 0
	v_addc_co_u32_e32 v67, vcc, 0, v99, vcc
	global_store_short v[66:67], v0, off
	v_cvt_pk_bf16_f32 v0, v83, s0
	global_store_short v[66:67], v0, off offset:1024
	v_cvt_pk_bf16_f32 v0, v84, s0
	global_store_short v[66:67], v0, off offset:2048
	v_cvt_pk_bf16_f32 v0, v85, s0
	global_store_short v[66:67], v0, off offset:3072
	v_add_co_u32_e32 v66, vcc, s9, v98
	v_cvt_pk_bf16_f32 v0, v86, s0
	s_nop 0
	v_addc_co_u32_e32 v67, vcc, 0, v99, vcc
	global_store_short v[66:67], v0, off
	v_cvt_pk_bf16_f32 v0, v87, s0
	global_store_short v[66:67], v0, off offset:1024
	v_cvt_pk_bf16_f32 v0, v88, s0
	global_store_short v[66:67], v0, off offset:2048
	v_cvt_pk_bf16_f32 v0, v89, s0
	global_store_short v[66:67], v0, off offset:3072
	v_add_co_u32_e32 v66, vcc, s10, v98
	v_cvt_pk_bf16_f32 v0, v90, s0
	s_nop 0
	v_addc_co_u32_e32 v67, vcc, 0, v99, vcc
	global_store_short v[66:67], v0, off
	v_cvt_pk_bf16_f32 v0, v91, s0
	global_store_short v[66:67], v0, off offset:1024
	v_cvt_pk_bf16_f32 v0, v92, s0
	s_waitcnt lgkmcnt(14)
	v_mfma_f32_32x32x16_bf16 v[18:33], v[158:161], v[154:157], v[18:33]
	global_store_short v[66:67], v0, off offset:2048
	v_cvt_pk_bf16_f32 v0, v93, s0
	global_store_short v[66:67], v0, off offset:3072
	v_add_co_u32_e32 v66, vcc, s11, v98
	v_cvt_pk_bf16_f32 v0, v94, s0
	s_nop 0
	v_addc_co_u32_e32 v67, vcc, 0, v99, vcc
	global_store_short v[66:67], v0, off
	v_cvt_pk_bf16_f32 v0, v95, s0
	global_store_short v[66:67], v0, off offset:1024
	v_cvt_pk_bf16_f32 v0, v96, s0
	global_store_short v[66:67], v0, off offset:2048
	v_cvt_pk_bf16_f32 v0, v97, s0
	s_add_u32 s0, s0, 0x10000
	s_addc_u32 s1, s1, 0
	s_add_i32 s2, s2, 4
	s_cmp_lg_u32 s0, 0x130000
	global_store_short v[66:67], v0, off offset:3072
	s_cbranch_scc1 .LBB0_1770
	v_readlane_b32 s0, v251, 12
	v_lshlrev_b64 v[66:67], 8, v[198:199]
	v_readlane_b32 s1, v251, 13
	s_nop 1
	v_lshl_add_u64 v[66:67], s[0:1], 0, v[66:67]
	global_store_dwordx4 v[66:67], v[2:5], off
	global_store_dwordx4 v[66:67], v[6:9], off offset:16
	global_store_dwordx4 v[66:67], v[10:13], off offset:32
	global_store_dwordx4 v[66:67], v[14:17], off offset:48
	global_store_dwordx4 v[66:67], v[50:53], off offset:64
	global_store_dwordx4 v[66:67], v[54:57], off offset:80
	global_store_dwordx4 v[66:67], v[58:61], off offset:96
	global_store_dwordx4 v[66:67], v[62:65], off offset:112
	global_store_dwordx4 v[66:67], v[34:37], off offset:128
	global_store_dwordx4 v[66:67], v[38:41], off offset:144
	global_store_dwordx4 v[66:67], v[42:45], off offset:160
	global_store_dwordx4 v[66:67], v[46:49], off offset:176
	global_store_dwordx4 v[66:67], v[18:21], off offset:192
	global_store_dwordx4 v[66:67], v[22:25], off offset:208
	global_store_dwordx4 v[66:67], v[26:29], off offset:224
	global_store_dwordx4 v[66:67], v[30:33], off offset:240
	s_waitcnt lgkmcnt(0)
	s_barrier
	v_readlane_b32 s10, v255, 22
	v_readlane_b32 s0, v255, 21
	s_nop 0
	s_cmp_lt_i32 s10, s0
	s_cbranch_scc1 .LBB0_1955

; DI void phase_inproj(const Params& p, int l, bool partB, int skipb, char* smem) {
;     ...
;   for (int idx = vblk >> 3; idx < per; idx += nvb >> 3) {
;     const int t = (vblk & 7) * per + idx;
;     const int mt = t / ntn; int tn = t % ntn;
;     if (partB) tn += 12; else if (tn >= 12) tn += 13;
;     inproj_tile(p, l, mt, tn, smem);
.LBB0_1954:
	v_readlane_b32 s0, v255, 20
	s_nop 0
	s_add_i32 s10, s10, s0
	v_readlane_b32 s0, v255, 21
	s_nop 0
	s_cmp_lt_i32 s10, s0
	s_waitcnt vmcnt(63) expcnt(7) lgkmcnt(15)
	s_barrier
	s_cbranch_scc0 .LBB0_1767
